# mixb: key-fragment loads for QK^T and the 20 V-row loads for P.V hoisted ahead of their use with counted vmcnt waits
# speedup vs baseline: 1.0546x; 1.0037x over previous
; DI int rowmap(int r, int lh) { return (r & 3) + 8 * (r >> 2) + 4 * lh; }
; DI f32x16 mfma(bf16x8 a, bf16x8 b, f32x16 c) { return __builtin_amdgcn_mfma_f32_32x32x16_bf16(a, b, c, 0, 0, 0); }
; DI f32x16 zero16() { f32x16 z; for (int i = 0; i < 16; ++i) z[i] = 0.f; return z; }
; DI void phase_mixb(const Prm& p, unsigned char* smem_raw, int S, int lgS, int& base) {
;     ...
;     const int wt = t * 8 + wave;
;     const int hg = wt & 1, g = (wt >> 1) % 3, blk = wt / 6;
;     const int seq = blk >> (lgS - 5), b_in = blk & ((S >> 5) - 1);
;     const int lgd = 2 * g, L = S >> lgd;
;     const int lgbpr = lgS - lgd - 5;
;     const int res = b_in >> lgbpr, i0 = (b_in & ((1 << lgbpr) - 1)) << 5;
;     const int tokbase = seq * S + res;
;     const int hd = g * 2 + hg, hc = hd * 64;
;     const int qi = i0 + lr;
;     const int qtok = tokbase + (qi << lgd);
;     bf16x8 qf[4];
; #pragma unroll
;     for (int ks = 0; ks < 4; ++ks) qf[ks] = *(const bf16x8*)(p.bqkv + (size_t)qtok * 1152 + hc + ks * 16 + lh * 8);
;     f32x16 sc[5];
; #pragma unroll
;     for (int tt = 0; tt < 5; ++tt) {
;       int ik = i0 - 64 + 32 * tt + lr;
;       ik = min(max(ik, 0), L - 1);
;       const u16* kp = p.bqkv + (size_t)(tokbase + (ik << lgd)) * 1152 + 384 + hc + lh * 8;
;       sc[tt] = zero16();
; #pragma unroll
;       for (int ks = 0; ks < 4; ++ks) sc[tt] = mfma(*(const bf16x8*)(kp + ks * 16), qf[ks], sc[tt]);
;     }
;     float mx = -1e30f;
; #pragma unroll
;     for (int tt = 0; tt < 5; ++tt)
; #pragma unroll
;       for (int r = 0; r < 16; ++r) {
;         const int ik = i0 - 64 + 32 * tt + rowmap(r, lh);
;         const int rel = ik - qi;
;         const bool valid = (rel >= -64) && (rel <= 64) && (ik >= 0) && (ik < L);
;         const int bi = min(max(rel + 64, 0), 128);
;         const float s = valid ? (sc[tt][r] * 0.125f + bt[hd * 129 + bi]) * LOG2E : -1e30f;
;         sc[tt][r] = s;
;         mx = fmaxf(mx, s);
.LBB0_1837:
	v_ashrrev_i32_e32 v2, 1, v128
	s_mov_b32 s2, 0x55555556
	v_mul_hi_i32 v3, v2, s2
	v_lshrrev_b32_e32 v4, 31, v3
	v_add_u32_e32 v3, v3, v4
	v_lshl_add_u32 v3, v3, 1, v3
	v_sub_u32_e32 v2, v2, v3
	v_mul_hi_i32 v3, v128, s82
	v_lshrrev_b32_e32 v4, 31, v3
	v_add_u32_e32 v3, v3, v4
	v_readlane_b32 s2, v254, 48
	v_lshlrev_b32_e32 v99, 1, v2
	v_or_b32_e32 v98, v99, v104
	v_ashrrev_i32_e32 v4, s2, v3
	v_readlane_b32 s2, v254, 50
	v_readlane_b32 s36, v253, 24
	v_lshlrev_b32_e32 v100, 6, v98
	v_and_b32_e32 v3, s2, v3
	v_readlane_b32 s2, v254, 51
	v_readlane_b32 s38, v253, 26
	v_readlane_b32 s39, v253, 27
	v_sub_u32_e32 v2, s2, v99
	v_add_u32_e32 v2, -5, v2
	s_waitcnt vmcnt(9)
	v_bfe_u32 v135, v3, 0, v2
	v_lshrrev_b32_e32 v5, v2, v3
	v_lshlrev_b32_e32 v133, 5, v135
	v_lshl_add_u32 v131, v4, s2, v5
	v_or_b32_e32 v97, v133, v95
	v_lshl_add_u32 v130, v97, v99, v131
	v_mov_b64_e32 v[6:7], s[38:39]
	s_movk_i32 s4, 0x900
	v_ashrrev_i32_e32 v101, 31, v100
	v_mad_i64_i32 v[2:3], s[2:3], v130, s4, v[6:7]
	v_lshlrev_b64 v[102:103], 1, v[100:101]
	v_lshl_add_u64 v[2:3], v[2:3], 0, v[102:103]
	v_readlane_b32 s2, v254, 49
	v_lshl_add_u64 v[8:9], v[2:3], 0, v[0:1]
	v_add_u32_e32 v14, v133, v105
	v_lshrrev_b32_e64 v134, v99, s2
	global_load_dwordx4 v[2:5], v[8:9], off
	global_load_dwordx4 v[90:93], v[8:9], off offset:32
	global_load_dwordx4 v[86:89], v[8:9], off offset:64
	global_load_dwordx4 v[82:85], v[8:9], off offset:96
	v_add_u32_e32 v132, -1, v134
	v_max_i32_e32 v8, 0, v14
	v_min_i32_e32 v8, v8, v132
	v_lshl_add_u32 v8, v8, v99, v131
	v_mad_i64_i32 v[8:9], s[2:3], v8, s4, v[6:7]
	v_lshl_add_u64 v[8:9], v[8:9], 0, v[102:103]
	v_lshl_add_u64 v[12:13], v[8:9], 0, v[0:1]
	global_load_dwordx4 v[144:147], v[12:13], off offset:768
	global_load_dwordx4 v[148:151], v[12:13], off offset:800
	global_load_dwordx4 v[152:155], v[12:13], off offset:832
	global_load_dwordx4 v[156:159], v[12:13], off offset:864
	v_max_i32_e32 v8, 0xffffffe0, v14
	v_add_u32_e32 v8, 32, v8
	v_min_i32_e32 v8, v8, v132
	v_lshl_add_u32 v8, v8, v99, v131
	v_mad_i64_i32 v[8:9], s[2:3], v8, s4, v[6:7]
	v_lshl_add_u64 v[8:9], v[8:9], 0, v[102:103]
	v_lshl_add_u64 v[136:137], v[8:9], 0, v[0:1]
	global_load_dwordx4 v[160:163], v[136:137], off offset:768
	global_load_dwordx4 v[164:167], v[136:137], off offset:800
	global_load_dwordx4 v[168:171], v[136:137], off offset:832
	global_load_dwordx4 v[172:175], v[136:137], off offset:864
	v_max_i32_e32 v8, 0xffffffc0, v14
	v_add_u32_e32 v8, 64, v8
	v_min_i32_e32 v8, v8, v132
	v_lshl_add_u32 v8, v8, v99, v131
	v_mad_i64_i32 v[8:9], s[2:3], v8, s4, v[6:7]
	v_lshl_add_u64 v[8:9], v[8:9], 0, v[102:103]
	v_lshl_add_u64 v[138:139], v[8:9], 0, v[0:1]
	global_load_dwordx4 v[176:179], v[138:139], off offset:768
	global_load_dwordx4 v[180:183], v[138:139], off offset:800
	global_load_dwordx4 v[184:187], v[138:139], off offset:832
	global_load_dwordx4 v[188:191], v[138:139], off offset:864
	v_max_i32_e32 v8, 0xffffffa0, v14
	v_add_u32_e32 v8, 0x60, v8
	v_min_i32_e32 v8, v8, v132
	v_lshl_add_u32 v8, v8, v99, v131
	v_mad_i64_i32 v[8:9], s[2:3], v8, s4, v[6:7]
	v_lshl_add_u64 v[8:9], v[8:9], 0, v[102:103]
	v_lshl_add_u64 v[140:141], v[8:9], 0, v[0:1]
	global_load_dwordx4 v[192:195], v[140:141], off offset:768
	global_load_dwordx4 v[196:199], v[140:141], off offset:800
	global_load_dwordx4 v[200:203], v[140:141], off offset:832
	global_load_dwordx4 v[204:207], v[140:141], off offset:864
	v_max_i32_e32 v8, 0xffffff80, v14
	v_add_u32_e32 v8, 0x80, v8
	v_min_i32_e32 v8, v8, v132
	v_lshl_add_u32 v8, v8, v99, v131
	v_mad_i64_i32 v[8:9], s[2:3], v8, s4, v[6:7]
	v_lshl_add_u64 v[8:9], v[8:9], 0, v[102:103]
	v_lshl_add_u64 v[142:143], v[8:9], 0, v[0:1]
	global_load_dwordx4 v[208:211], v[142:143], off offset:768
	global_load_dwordx4 v[212:215], v[142:143], off offset:800
	global_load_dwordx4 v[216:219], v[142:143], off offset:832
	global_load_dwordx4 v[220:223], v[142:143], off offset:864
	v_cmp_lt_u32_e32 vcc, 1, v135
	v_readlane_b32 s37, v253, 25
	v_readlane_b32 s40, v253, 28
	v_readlane_b32 s41, v253, 29
	v_readlane_b32 s42, v253, 30
	v_readlane_b32 s43, v253, 31
	v_readlane_b32 s44, v253, 32
	v_readlane_b32 s45, v253, 33
	v_readlane_b32 s46, v253, 34
	v_readlane_b32 s47, v253, 35
	v_readlane_b32 s48, v253, 36
	v_readlane_b32 s49, v253, 37
	v_readlane_b32 s50, v253, 38
	v_readlane_b32 s51, v253, 39
	s_waitcnt vmcnt(16)
	v_mfma_f32_32x32x16_bf16 v[66:81], v[144:147], v[2:5], 0
	v_mfma_f32_32x32x16_bf16 v[66:81], v[148:151], v[90:93], v[66:81]
	v_mfma_f32_32x32x16_bf16 v[66:81], v[152:155], v[86:89], v[66:81]
	v_mfma_f32_32x32x16_bf16 v[66:81], v[156:159], v[82:85], v[66:81]
	s_waitcnt vmcnt(12)
	v_mfma_f32_32x32x16_bf16 v[50:65], v[160:163], v[2:5], 0
	v_mfma_f32_32x32x16_bf16 v[50:65], v[164:167], v[90:93], v[50:65]
	v_mfma_f32_32x32x16_bf16 v[50:65], v[168:171], v[86:89], v[50:65]
	v_mfma_f32_32x32x16_bf16 v[50:65], v[172:175], v[82:85], v[50:65]
	s_waitcnt vmcnt(8)
	v_mfma_f32_32x32x16_bf16 v[34:49], v[176:179], v[2:5], 0
	v_mfma_f32_32x32x16_bf16 v[34:49], v[180:183], v[90:93], v[34:49]
	v_mfma_f32_32x32x16_bf16 v[34:49], v[184:187], v[86:89], v[34:49]
	v_mfma_f32_32x32x16_bf16 v[34:49], v[188:191], v[82:85], v[34:49]
	s_waitcnt vmcnt(4)
	v_mfma_f32_32x32x16_bf16 v[18:33], v[192:195], v[2:5], 0
	v_mfma_f32_32x32x16_bf16 v[18:33], v[196:199], v[90:93], v[18:33]
	v_mfma_f32_32x32x16_bf16 v[18:33], v[200:203], v[86:89], v[18:33]
	v_mfma_f32_32x32x16_bf16 v[18:33], v[204:207], v[82:85], v[18:33]
	s_waitcnt vmcnt(0)
	v_mfma_f32_32x32x16_bf16 v[2:17], v[208:211], v[2:5], 0
	v_mfma_f32_32x32x16_bf16 v[2:17], v[212:215], v[90:93], v[2:17]
	v_mfma_f32_32x32x16_bf16 v[2:17], v[216:219], v[86:89], v[2:17]
	v_mfma_f32_32x32x16_bf16 v[2:17], v[220:223], v[82:85], v[2:17]
	v_subrev_u32_e32 v82, 64, v133
	v_or_b32_e32 v87, v82, v94
	v_sub_u32_e32 v83, v87, v97
	v_add_u32_e32 v86, 64, v83
	v_cmp_gt_u32_e64 s[2:3], s73, v86
	v_cmp_lt_i32_e64 s[4:5], v87, v134
	s_and_b64 s[2:3], s[4:5], s[2:3]
	v_mul_i32_i24_e32 v85, 0x204, v98
	s_and_b64 s[4:5], vcc, s[2:3]
	v_mov_b32_e32 v83, 0xf149f2ca
	v_mov_b32_e32 v84, 0xf149f2ca
	s_and_saveexec_b64 s[2:3], s[4:5]
	s_cbranch_execz .LBB0_1839
	v_lshl_add_u32 v84, v86, 2, v85
	ds_read_b32 v84, v84
	s_waitcnt lgkmcnt(0)
	v_fmac_f32_e32 v84, 0x3e000000, v66
	v_mul_f32_e32 v84, 0x3fb8aa3b, v84

; DI int rowmap(int r, int lh) { return (r & 3) + 8 * (r >> 2) + 4 * lh; }
; DI float ex2(float x) { return __builtin_amdgcn_exp2f(x); }
; DI void phase_mixb(const Prm& p, unsigned char* smem_raw, int S, int lgS, int& base) {
;     ...
;     float mx = -1e30f;
; #pragma unroll
;     for (int tt = 0; tt < 5; ++tt)
; #pragma unroll
;       for (int r = 0; r < 16; ++r) {
;         const int ik = i0 - 64 + 32 * tt + rowmap(r, lh);
;         const int rel = ik - qi;
;         const bool valid = (rel >= -64) && (rel <= 64) && (ik >= 0) && (ik < L);
;         const int bi = min(max(rel + 64, 0), 128);
;         const float s = valid ? (sc[tt][r] * 0.125f + bt[hd * 129 + bi]) * LOG2E : -1e30f;
;         sc[tt][r] = s;
;         mx = fmaxf(mx, s);
;       }
;     mx = fmaxf(mx, __shfl_xor(mx, 32));
;     float sum = 0.f;
; #pragma unroll
;     for (int tt = 0; tt < 5; ++tt)
; #pragma unroll
;       for (int r = 0; r < 16; ++r) {
;         const float pv = ex2(sc[tt][r] - mx);
;         sum += pv;
;         sc[tt][r] = pv;
;       }
;     sum += __shfl_xor(sum, 32);
.LBB0_1997:
	s_or_b64 exec, exec, s[2:3]
	s_mov_b32 s2, 0xf149f2ca
	v_max3_f32 v2, v84, s2, v83
	v_max3_f32 v2, v2, v86, v67
	v_max3_f32 v2, v2, v69, v68
	v_max3_f32 v2, v2, v71, v70
	v_max3_f32 v2, v2, v73, v72
	v_max3_f32 v2, v2, v75, v74
	v_max3_f32 v2, v2, v77, v76
	v_max3_f32 v2, v2, v79, v78
	v_max3_f32 v2, v2, v81, v80
	v_max3_f32 v2, v2, v51, v50
	v_max3_f32 v2, v2, v53, v52
	v_max3_f32 v2, v2, v55, v54
	v_max3_f32 v2, v2, v57, v56
	v_max3_f32 v2, v2, v59, v58
	v_max3_f32 v2, v2, v61, v60
	v_max3_f32 v2, v2, v63, v62
	v_max3_f32 v2, v2, v65, v64
	v_max3_f32 v2, v2, v35, v34
	v_max3_f32 v2, v2, v87, v88
	v_max3_f32 v2, v2, v89, v39
	v_max3_f32 v2, v2, v41, v40
	v_max3_f32 v2, v2, v43, v42
	v_max3_f32 v2, v2, v45, v44
	v_max3_f32 v2, v2, v47, v46
	v_max3_f32 v2, v2, v49, v48
	v_max3_f32 v2, v2, v19, v18
	v_max3_f32 v2, v2, v21, v20
	v_max3_f32 v2, v2, v23, v22
	v_max3_f32 v2, v2, v25, v24
	v_max3_f32 v2, v2, v27, v26
	v_max3_f32 v2, v2, v29, v28
	v_max3_f32 v2, v2, v31, v30
	v_max3_f32 v2, v2, v33, v32
	v_max3_f32 v2, v2, v156, v91
	v_max3_f32 v2, v2, v158, v157
	v_max3_f32 v2, v2, v160, v159
	v_max3_f32 v2, v2, v162, v161
	v_max3_f32 v2, v2, v11, v10
	v_max3_f32 v2, v2, v13, v12
	v_max3_f32 v2, v2, v15, v14
	ds_bpermute_b32 v3, v106, v2
	v_readlane_b32 s36, v253, 24
	v_readlane_b32 s38, v253, 26
	v_readlane_b32 s39, v253, 27
	s_movk_i32 s4, 0x900
	s_waitcnt lgkmcnt(0)
	v_max_f32_e32 v3, v3, v3
	v_max_f32_e32 v36, v2, v3
	v_sub_f32_e32 v2, v84, v36
	v_exp_f32_e32 v2, v2
	v_sub_f32_e32 v3, v83, v36
	v_exp_f32_e32 v3, v3
	v_sub_f32_e32 v17, v73, v36
	v_add_f32_e32 v4, 0, v2
	v_exp_f32_e32 v148, v17
	v_add_f32_e32 v5, v3, v4
	v_sub_f32_e32 v4, v86, v36
	v_exp_f32_e32 v4, v4
	v_sub_f32_e32 v17, v72, v36
	v_exp_f32_e32 v149, v17
	v_sub_f32_e32 v17, v75, v36
	v_add_f32_e32 v6, v4, v5
	v_sub_f32_e32 v5, v67, v36
	v_exp_f32_e32 v5, v5
	v_exp_f32_e32 v150, v17
	v_sub_f32_e32 v17, v74, v36
	v_exp_f32_e32 v151, v17
	v_add_f32_e32 v7, v5, v6
	v_sub_f32_e32 v6, v69, v36
	v_exp_f32_e32 v6, v6
	v_sub_f32_e32 v17, v77, v36
	v_exp_f32_e32 v152, v17
	v_sub_f32_e32 v17, v76, v36
	v_add_f32_e32 v8, v6, v7
	v_sub_f32_e32 v7, v68, v36
	v_exp_f32_e32 v7, v7
	v_exp_f32_e32 v153, v17
	v_sub_f32_e32 v17, v79, v36
	v_exp_f32_e32 v154, v17
	v_add_f32_e32 v9, v7, v8
	v_sub_f32_e32 v8, v71, v36
	v_exp_f32_e32 v8, v8
	v_sub_f32_e32 v17, v78, v36
	v_exp_f32_e32 v155, v17
	v_sub_f32_e32 v17, v81, v36
	v_add_f32_e32 v16, v8, v9
	v_sub_f32_e32 v9, v70, v36
	v_exp_f32_e32 v9, v9
	v_exp_f32_e32 v137, v17
	v_sub_f32_e32 v17, v80, v36
	v_exp_f32_e32 v140, v17
	v_add_f32_e32 v16, v9, v16
	v_add_f32_e32 v16, v148, v16
	v_add_f32_e32 v16, v149, v16
	v_add_f32_e32 v16, v150, v16
	v_add_f32_e32 v16, v151, v16
	v_add_f32_e32 v16, v152, v16
	v_add_f32_e32 v16, v153, v16
	v_sub_f32_e32 v17, v51, v36
	v_add_f32_e32 v16, v154, v16
	v_exp_f32_e32 v141, v17
	v_sub_f32_e32 v17, v50, v36
	v_add_f32_e32 v16, v155, v16
	v_exp_f32_e32 v143, v17
	v_sub_f32_e32 v17, v53, v36
	v_add_f32_e32 v16, v137, v16
	v_exp_f32_e32 v144, v17
	v_sub_f32_e32 v17, v52, v36
	v_add_f32_e32 v16, v140, v16
	v_exp_f32_e32 v145, v17
	v_sub_f32_e32 v17, v55, v36
	v_add_f32_e32 v16, v141, v16
	v_exp_f32_e32 v146, v17
	v_sub_f32_e32 v17, v54, v36
	v_add_f32_e32 v16, v143, v16
	v_exp_f32_e32 v147, v17
	v_sub_f32_e32 v17, v57, v36
	v_add_f32_e32 v16, v144, v16
	v_exp_f32_e32 v92, v17
	v_sub_f32_e32 v17, v56, v36
	v_add_f32_e32 v16, v145, v16
	v_exp_f32_e32 v93, v17
	v_sub_f32_e32 v17, v59, v36
	v_add_f32_e32 v16, v146, v16
	v_exp_f32_e32 v134, v17
	v_sub_f32_e32 v17, v58, v36
	v_add_f32_e32 v16, v147, v16
	v_exp_f32_e32 v135, v17
	v_sub_f32_e32 v17, v61, v36
	v_add_f32_e32 v16, v92, v16
	v_exp_f32_e32 v136, v17
	v_sub_f32_e32 v17, v60, v36
	v_add_f32_e32 v16, v93, v16
	v_exp_f32_e32 v138, v17
	v_sub_f32_e32 v17, v63, v36
	v_add_f32_e32 v16, v134, v16
	v_exp_f32_e32 v139, v17
	v_sub_f32_e32 v17, v62, v36
	v_add_f32_e32 v16, v135, v16
	v_exp_f32_e32 v142, v17
	v_sub_f32_e32 v17, v65, v36
	v_add_f32_e32 v16, v136, v16
	v_exp_f32_e32 v79, v17
	v_sub_f32_e32 v17, v64, v36
	v_add_f32_e32 v16, v138, v16
	v_exp_f32_e32 v83, v17
	v_sub_f32_e32 v17, v35, v36
	v_add_f32_e32 v16, v139, v16
	v_exp_f32_e32 v84, v17
	v_sub_f32_e32 v17, v34, v36
	v_add_f32_e32 v16, v142, v16
	v_exp_f32_e32 v86, v17
	v_sub_f32_e32 v17, v87, v36
	v_add_f32_e32 v16, v79, v16
	v_exp_f32_e32 v87, v17
	v_sub_f32_e32 v17, v88, v36
	v_add_f32_e32 v16, v83, v16
	v_exp_f32_e32 v88, v17
	v_sub_f32_e32 v17, v89, v36
	v_add_f32_e32 v16, v84, v16
	v_exp_f32_e32 v89, v17
	v_sub_f32_e32 v17, v39, v36
	v_add_f32_e32 v16, v86, v16
	v_exp_f32_e32 v90, v17
	v_sub_f32_e32 v17, v41, v36
	v_add_f32_e32 v16, v87, v16
	v_exp_f32_e32 v74, v17
	v_sub_f32_e32 v17, v40, v36
	v_add_f32_e32 v16, v88, v16
	v_exp_f32_e32 v75, v17
	v_sub_f32_e32 v17, v43, v36
	v_add_f32_e32 v16, v89, v16
	v_exp_f32_e32 v76, v17
	v_sub_f32_e32 v17, v42, v36
	v_add_f32_e32 v16, v90, v16
	v_exp_f32_e32 v77, v17
	v_sub_f32_e32 v17, v45, v36
	v_add_f32_e32 v16, v74, v16
	v_exp_f32_e32 v78, v17
	v_sub_f32_e32 v17, v44, v36
	v_add_f32_e32 v16, v75, v16
	v_exp_f32_e32 v80, v17
	v_sub_f32_e32 v17, v47, v36
	v_add_f32_e32 v16, v76, v16
	v_exp_f32_e32 v81, v17
	v_sub_f32_e32 v17, v46, v36
	v_add_f32_e32 v16, v77, v16
	v_exp_f32_e32 v85, v17
	v_sub_f32_e32 v17, v49, v36
	v_add_f32_e32 v16, v78, v16
	v_exp_f32_e32 v62, v17
	v_sub_f32_e32 v17, v48, v36
	v_add_f32_e32 v16, v80, v16
	v_exp_f32_e32 v65, v17
	v_sub_f32_e32 v17, v19, v36
	v_add_f32_e32 v16, v81, v16
	v_exp_f32_e32 v67, v17
	v_sub_f32_e32 v17, v18, v36
	v_add_f32_e32 v16, v85, v16
	v_exp_f32_e32 v69, v17
	v_sub_f32_e32 v17, v21, v36
; DI f32x16 zero16() { f32x16 z; for (int i = 0; i < 16; ++i) z[i] = 0.f; return z; }
; DI float ex2(float x) { return __builtin_amdgcn_exp2f(x); }
; DI void phase_mixb(const Prm& p, unsigned char* smem_raw, int S, int lgS, int& base) {
;     ...
;     for (int tt = 0; tt < 5; ++tt)
; #pragma unroll
;       for (int r = 0; r < 16; ++r) {
;         const float pv = ex2(sc[tt][r] - mx);
;         sum += pv;
;         sc[tt][r] = pv;
;       }
;     sum += __shfl_xor(sum, 32);
;     f32x16 oacc[2];
;     oacc[0] = zero16(); oacc[1] = zero16();
; #pragma unroll
;     for (int tt = 0; tt < 5; ++tt) {
; #pragma unroll
;       for (int e = 0; e < 4; ++e) {
;         const int c = lane + 64 * e, key = c >> 3, dch = c & 7;
;         int ik = i0 - 64 + 32 * tt + key;
;         ik = min(max(ik, 0), L - 1);
;         const u32x4 raw = *(const u32x4*)(p.bqkv + (size_t)(tokbase + (ik << lgd)) * 1152 + 768 + hc + dch * 8);
	v_add_f32_e32 v16, v62, v16
	v_exp_f32_e32 v70, v17
	v_sub_f32_e32 v17, v20, v36
	v_add_f32_e32 v16, v65, v16
	v_exp_f32_e32 v71, v17
	v_sub_f32_e32 v17, v23, v36
	v_add_f32_e32 v16, v67, v16
	v_exp_f32_e32 v72, v17
	v_sub_f32_e32 v17, v22, v36
	v_add_f32_e32 v16, v69, v16
	v_exp_f32_e32 v73, v17
	v_sub_f32_e32 v17, v25, v36
	v_add_f32_e32 v16, v70, v16
	v_exp_f32_e32 v57, v17
	v_sub_f32_e32 v17, v24, v36
	v_add_f32_e32 v16, v71, v16
	v_exp_f32_e32 v58, v17
	v_sub_f32_e32 v17, v27, v36
	v_add_f32_e32 v16, v72, v16
	v_exp_f32_e32 v59, v17
	v_sub_f32_e32 v17, v26, v36
	v_add_f32_e32 v16, v73, v16
	v_exp_f32_e32 v60, v17
	v_sub_f32_e32 v17, v29, v36
	v_add_f32_e32 v16, v57, v16
	v_exp_f32_e32 v61, v17
	v_sub_f32_e32 v17, v28, v36
	v_add_f32_e32 v16, v58, v16
	v_exp_f32_e32 v63, v17
	v_sub_f32_e32 v17, v31, v36
	v_add_f32_e32 v16, v59, v16
	v_exp_f32_e32 v64, v17
	v_sub_f32_e32 v17, v30, v36
	v_add_f32_e32 v16, v60, v16
	v_exp_f32_e32 v68, v17
	v_sub_f32_e32 v17, v33, v36
	v_add_f32_e32 v16, v61, v16
	v_exp_f32_e32 v49, v17
	v_sub_f32_e32 v17, v32, v36
	v_add_f32_e32 v16, v63, v16
	v_exp_f32_e32 v50, v17
	v_sub_f32_e32 v17, v156, v36
	v_add_f32_e32 v16, v64, v16
	v_exp_f32_e32 v51, v17
	v_sub_f32_e32 v17, v91, v36
	v_add_f32_e32 v16, v68, v16
	v_exp_f32_e32 v52, v17
	v_sub_f32_e32 v17, v158, v36
	v_add_f32_e32 v16, v49, v16
	v_exp_f32_e32 v53, v17
	v_sub_f32_e32 v17, v157, v36
	v_add_f32_e32 v16, v50, v16
	v_exp_f32_e32 v54, v17
	v_sub_f32_e32 v17, v160, v36
	v_add_f32_e32 v16, v51, v16
	v_exp_f32_e32 v55, v17
	v_sub_f32_e32 v17, v159, v36
	v_add_f32_e32 v16, v52, v16
	v_exp_f32_e32 v56, v17
	v_sub_f32_e32 v17, v162, v36
	v_add_f32_e32 v16, v53, v16
	v_exp_f32_e32 v41, v17
	v_sub_f32_e32 v17, v161, v36
	v_add_f32_e32 v16, v54, v16
	v_exp_f32_e32 v42, v17
	v_sub_f32_e32 v11, v11, v36
	v_add_f32_e32 v16, v55, v16
	v_exp_f32_e32 v43, v11
	v_sub_f32_e32 v10, v10, v36
	v_add_f32_e32 v16, v56, v16
	v_exp_f32_e32 v44, v10
	v_add_f32_e32 v16, v41, v16
	v_add_f32_e32 v16, v42, v16
	v_add_f32_e32 v11, v43, v16
	v_add_f32_e32 v10, v44, v11
	v_sub_f32_e32 v11, v13, v36
	v_exp_f32_e32 v45, v11
	v_sub_f32_e32 v11, v12, v36
	v_exp_f32_e32 v46, v11
	v_sub_f32_e32 v11, v15, v36
	v_exp_f32_e32 v47, v11
	v_sub_f32_e32 v11, v14, v36
	v_exp_f32_e32 v48, v11
	v_add_f32_e32 v10, v45, v10
	v_add_f32_e32 v10, v46, v10
	v_add_f32_e32 v10, v47, v10
	v_add_f32_e32 v39, v48, v10
	v_mov_b64_e32 v[156:157], s[38:39]
	v_mov_b32_e32 v158, v96
	v_mov_b32_e32 v159, v1
	v_or_b32_e32 v40, v82, v108
	v_max_i32_e32 v40, 0, v40
	v_min_i32_e32 v40, v40, v132
	v_lshl_add_u32 v40, v40, v99, v131
	v_mad_i64_i32 v[14:15], s[2:3], v40, s4, v[156:157]
	v_lshl_add_u64 v[14:15], v[14:15], 0, v[102:103]
	v_lshl_add_u64 v[14:15], v[14:15], 0, v[158:159]
	global_load_dwordx4 v[160:163], v[14:15], off offset:1536
	v_or_b32_e32 v40, v82, v110
	v_max_i32_e32 v40, 0, v40
	v_min_i32_e32 v40, v40, v132
	v_lshl_add_u32 v40, v40, v99, v131
	v_mad_i64_i32 v[14:15], s[2:3], v40, s4, v[156:157]
	v_lshl_add_u64 v[14:15], v[14:15], 0, v[102:103]
	v_lshl_add_u64 v[14:15], v[14:15], 0, v[158:159]
	global_load_dwordx4 v[164:167], v[14:15], off offset:1536
	v_or_b32_e32 v40, v82, v111
	v_max_i32_e32 v40, 0, v40
	v_min_i32_e32 v40, v40, v132
	v_lshl_add_u32 v40, v40, v99, v131
	v_mad_i64_i32 v[14:15], s[2:3], v40, s4, v[156:157]
	v_lshl_add_u64 v[14:15], v[14:15], 0, v[102:103]
	v_lshl_add_u64 v[14:15], v[14:15], 0, v[158:159]
	global_load_dwordx4 v[168:171], v[14:15], off offset:1536
	v_or_b32_e32 v40, v82, v112
	v_max_i32_e32 v40, 0, v40
	v_min_i32_e32 v40, v40, v132
	v_lshl_add_u32 v40, v40, v99, v131
	v_mad_i64_i32 v[14:15], s[2:3], v40, s4, v[156:157]
	v_lshl_add_u64 v[14:15], v[14:15], 0, v[102:103]
	v_lshl_add_u64 v[14:15], v[14:15], 0, v[158:159]
	global_load_dwordx4 v[172:175], v[14:15], off offset:1536
	v_or_b32_e32 v40, v66, v108
	v_max_i32_e32 v40, 0, v40
	v_min_i32_e32 v40, v40, v132
	v_lshl_add_u32 v40, v40, v99, v131
	v_mad_i64_i32 v[14:15], s[2:3], v40, s4, v[156:157]
	v_lshl_add_u64 v[14:15], v[14:15], 0, v[102:103]
	v_lshl_add_u64 v[14:15], v[14:15], 0, v[158:159]
	global_load_dwordx4 v[176:179], v[14:15], off offset:1536
	v_or_b32_e32 v40, v66, v110
	v_max_i32_e32 v40, 0, v40
	v_min_i32_e32 v40, v40, v132
	v_lshl_add_u32 v40, v40, v99, v131
	v_mad_i64_i32 v[14:15], s[2:3], v40, s4, v[156:157]
	v_lshl_add_u64 v[14:15], v[14:15], 0, v[102:103]
	v_lshl_add_u64 v[14:15], v[14:15], 0, v[158:159]
	global_load_dwordx4 v[180:183], v[14:15], off offset:1536
	v_or_b32_e32 v40, v66, v111
	v_max_i32_e32 v40, 0, v40
	v_min_i32_e32 v40, v40, v132
	v_lshl_add_u32 v40, v40, v99, v131
	v_mad_i64_i32 v[14:15], s[2:3], v40, s4, v[156:157]
	v_lshl_add_u64 v[14:15], v[14:15], 0, v[102:103]
	v_lshl_add_u64 v[14:15], v[14:15], 0, v[158:159]
	global_load_dwordx4 v[184:187], v[14:15], off offset:1536
	v_or_b32_e32 v40, v66, v112
	v_max_i32_e32 v40, 0, v40
	v_min_i32_e32 v40, v40, v132
	v_lshl_add_u32 v40, v40, v99, v131
	v_mad_i64_i32 v[14:15], s[2:3], v40, s4, v[156:157]
	v_lshl_add_u64 v[14:15], v[14:15], 0, v[102:103]
	v_lshl_add_u64 v[14:15], v[14:15], 0, v[158:159]
	global_load_dwordx4 v[188:191], v[14:15], off offset:1536
	v_or_b32_e32 v40, v133, v108
	v_max_i32_e32 v40, 0, v40
	v_min_i32_e32 v40, v40, v132
	v_lshl_add_u32 v40, v40, v99, v131
	v_mad_i64_i32 v[14:15], s[2:3], v40, s4, v[156:157]
	v_lshl_add_u64 v[14:15], v[14:15], 0, v[102:103]
	v_lshl_add_u64 v[14:15], v[14:15], 0, v[158:159]
	global_load_dwordx4 v[192:195], v[14:15], off offset:1536
	v_or_b32_e32 v40, v133, v110
	v_max_i32_e32 v40, 0, v40
	v_min_i32_e32 v40, v40, v132
	v_lshl_add_u32 v40, v40, v99, v131
	v_mad_i64_i32 v[14:15], s[2:3], v40, s4, v[156:157]
; DI f32x16 mfma(bf16x8 a, bf16x8 b, f32x16 c) { return __builtin_amdgcn_mfma_f32_32x32x16_bf16(a, b, c, 0, 0, 0); }
; DI void phase_mixb(const Prm& p, unsigned char* smem_raw, int S, int lgS, int& base) {
;     ...
;     for (int tt = 0; tt < 5; ++tt) {
; #pragma unroll
;       for (int e = 0; e < 4; ++e) {
;         const int c = lane + 64 * e, key = c >> 3, dch = c & 7;
;         int ik = i0 - 64 + 32 * tt + key;
;         ik = min(max(ik, 0), L - 1);
;         const u32x4 raw = *(const u32x4*)(p.bqkv + (size_t)(tokbase + (ik << lgd)) * 1152 + 768 + hc + dch * 8);
; #pragma unroll
;         for (int jj = 0; jj < 4; ++jj) {
;           vt[(dch * 8 + 2 * jj) * 40 + key] = (u16)(raw[jj] & 0xffffu);
;           vt[(dch * 8 + 2 * jj + 1) * 40 + key] = (u16)(raw[jj] >> 16);
;         }
;       }
;       __syncthreads();
; #pragma unroll
;       for (int u = 0; u < 2; ++u) {
;         u32x4 pk;
; #pragma unroll
;         for (int jj = 0; jj < 4; ++jj) pk[jj] = pack2(sc[tt][8 * u + 2 * jj], sc[tt][8 * u + 2 * jj + 1]);
;         const bf16x8 pf = __builtin_bit_cast(bf16x8, pk);
; #pragma unroll
;         for (int dt = 0; dt < 2; ++dt) {
;           const u16* vp = vt + (dt * 32 + lr) * 40 + 16 * u + 4 * lh;
;           u32x4 vv;
;           const u32x2 lo = *(const u32x2*)vp, hi = *(const u32x2*)(vp + 8);
;           vv[0] = lo[0]; vv[1] = lo[1]; vv[2] = hi[0]; vv[3] = hi[1];
;           oacc[dt] = mfma(__builtin_bit_cast(bf16x8, vv), pf, oacc[dt]);
;         }
;       }
	v_lshl_add_u64 v[14:15], v[14:15], 0, v[102:103]
	v_lshl_add_u64 v[14:15], v[14:15], 0, v[158:159]
	global_load_dwordx4 v[196:199], v[14:15], off offset:1536
	v_or_b32_e32 v40, v133, v111
	v_max_i32_e32 v40, 0, v40
	v_min_i32_e32 v40, v40, v132
	v_lshl_add_u32 v40, v40, v99, v131
	v_mad_i64_i32 v[14:15], s[2:3], v40, s4, v[156:157]
	v_lshl_add_u64 v[14:15], v[14:15], 0, v[102:103]
	v_lshl_add_u64 v[14:15], v[14:15], 0, v[158:159]
	global_load_dwordx4 v[200:203], v[14:15], off offset:1536
	v_or_b32_e32 v40, v133, v112
	v_max_i32_e32 v40, 0, v40
	v_min_i32_e32 v40, v40, v132
	v_lshl_add_u32 v40, v40, v99, v131
	v_mad_i64_i32 v[14:15], s[2:3], v40, s4, v[156:157]
	v_lshl_add_u64 v[14:15], v[14:15], 0, v[102:103]
	v_lshl_add_u64 v[14:15], v[14:15], 0, v[158:159]
	global_load_dwordx4 v[204:207], v[14:15], off offset:1536
	v_or_b32_e32 v40, v38, v108
	v_max_i32_e32 v40, 0, v40
	v_min_i32_e32 v40, v40, v132
	v_lshl_add_u32 v40, v40, v99, v131
	v_mad_i64_i32 v[14:15], s[2:3], v40, s4, v[156:157]
	v_lshl_add_u64 v[14:15], v[14:15], 0, v[102:103]
	v_lshl_add_u64 v[14:15], v[14:15], 0, v[158:159]
	global_load_dwordx4 v[208:211], v[14:15], off offset:1536
	v_or_b32_e32 v40, v38, v110
	v_max_i32_e32 v40, 0, v40
	v_min_i32_e32 v40, v40, v132
	v_lshl_add_u32 v40, v40, v99, v131
	v_mad_i64_i32 v[14:15], s[2:3], v40, s4, v[156:157]
	v_lshl_add_u64 v[14:15], v[14:15], 0, v[102:103]
	v_lshl_add_u64 v[14:15], v[14:15], 0, v[158:159]
	global_load_dwordx4 v[212:215], v[14:15], off offset:1536
	v_or_b32_e32 v40, v38, v111
	v_max_i32_e32 v40, 0, v40
	v_min_i32_e32 v40, v40, v132
	v_lshl_add_u32 v40, v40, v99, v131
	v_mad_i64_i32 v[14:15], s[2:3], v40, s4, v[156:157]
	v_lshl_add_u64 v[14:15], v[14:15], 0, v[102:103]
	v_lshl_add_u64 v[14:15], v[14:15], 0, v[158:159]
	global_load_dwordx4 v[216:219], v[14:15], off offset:1536
	v_or_b32_e32 v40, v38, v112
	v_max_i32_e32 v40, 0, v40
	v_min_i32_e32 v40, v40, v132
	v_lshl_add_u32 v40, v40, v99, v131
	v_mad_i64_i32 v[14:15], s[2:3], v40, s4, v[156:157]
	v_lshl_add_u64 v[14:15], v[14:15], 0, v[102:103]
	v_lshl_add_u64 v[14:15], v[14:15], 0, v[158:159]
	global_load_dwordx4 v[220:223], v[14:15], off offset:1536
	v_or_b32_e32 v40, v37, v108
	v_max_i32_e32 v40, 0, v40
	v_min_i32_e32 v40, v40, v132
	v_lshl_add_u32 v40, v40, v99, v131
	v_mad_i64_i32 v[14:15], s[2:3], v40, s4, v[156:157]
	v_lshl_add_u64 v[14:15], v[14:15], 0, v[102:103]
	v_lshl_add_u64 v[14:15], v[14:15], 0, v[158:159]
	global_load_dwordx4 v[226:229], v[14:15], off offset:1536
	v_or_b32_e32 v40, v37, v110
	v_max_i32_e32 v40, 0, v40
	v_min_i32_e32 v40, v40, v132
	v_lshl_add_u32 v40, v40, v99, v131
	v_mad_i64_i32 v[14:15], s[2:3], v40, s4, v[156:157]
	v_lshl_add_u64 v[14:15], v[14:15], 0, v[102:103]
	v_lshl_add_u64 v[14:15], v[14:15], 0, v[158:159]
	global_load_dwordx4 v[234:237], v[14:15], off offset:1536
	v_or_b32_e32 v40, v37, v111
	v_max_i32_e32 v40, 0, v40
	v_min_i32_e32 v40, v40, v132
	v_lshl_add_u32 v40, v40, v99, v131
	v_mad_i64_i32 v[14:15], s[2:3], v40, s4, v[156:157]
	v_lshl_add_u64 v[14:15], v[14:15], 0, v[102:103]
	v_lshl_add_u64 v[14:15], v[14:15], 0, v[158:159]
	global_load_dwordx4 v[244:247], v[14:15], off offset:1536
	v_or_b32_e32 v40, v37, v112
	v_max_i32_e32 v40, 0, v40
	v_min_i32_e32 v40, v40, v132
	v_lshl_add_u32 v40, v40, v99, v131
	v_mad_i64_i32 v[14:15], s[2:3], v40, s4, v[156:157]
	v_lshl_add_u64 v[14:15], v[14:15], 0, v[102:103]
	v_lshl_add_u64 v[14:15], v[14:15], 0, v[158:159]
	global_load_dwordx4 v[248:251], v[14:15], off offset:1536
	v_mov_b64_e32 v[34:35], s[38:39]
	v_mov_b32_e32 v97, v1
	s_waitcnt vmcnt(19)
	ds_write_b16 v109, v160 offset:3328
	ds_write_b16_d16_hi v109, v160 offset:3408
	ds_write_b16 v109, v161 offset:3488
	ds_write_b16_d16_hi v109, v161 offset:3568
	ds_write_b16 v109, v162 offset:3648
	ds_write_b16_d16_hi v109, v162 offset:3728
	ds_write_b16 v109, v163 offset:3808
	ds_write_b16_d16_hi v109, v163 offset:3888
	s_waitcnt vmcnt(18)
	ds_write_b16 v109, v164 offset:3344
	ds_write_b16_d16_hi v109, v164 offset:3424
	ds_write_b16 v109, v165 offset:3504
	ds_write_b16_d16_hi v109, v165 offset:3584
	ds_write_b16 v109, v166 offset:3664
	ds_write_b16_d16_hi v109, v166 offset:3744
	ds_write_b16 v109, v167 offset:3824
	ds_write_b16_d16_hi v109, v167 offset:3904
	s_waitcnt vmcnt(17)
	ds_write_b16 v109, v168 offset:3360
	ds_write_b16_d16_hi v109, v168 offset:3440
	ds_write_b16 v109, v169 offset:3520
	ds_write_b16_d16_hi v109, v169 offset:3600
	ds_write_b16 v109, v170 offset:3680
	ds_write_b16_d16_hi v109, v170 offset:3760
	ds_write_b16 v109, v171 offset:3840
	ds_write_b16_d16_hi v109, v171 offset:3920
	v_add_u32_e32 v91, 0x800, v129
	s_waitcnt vmcnt(16)
	ds_write_b16 v109, v172 offset:3376
	ds_write_b16_d16_hi v109, v172 offset:3456
	ds_write_b16 v109, v173 offset:3536
	ds_write_b16_d16_hi v109, v173 offset:3616
	ds_write_b16 v109, v174 offset:3696
	ds_write_b16_d16_hi v109, v174 offset:3776
	ds_write_b16 v109, v175 offset:3856
	ds_write_b16_d16_hi v109, v175 offset:3936
	s_waitcnt lgkmcnt(0)
	s_barrier
	v_cvt_pk_bf16_f32 v2, v2, v3
	v_cvt_pk_bf16_f32 v3, v4, v5
	v_cvt_pk_bf16_f32 v4, v6, v7
	v_cvt_pk_bf16_f32 v5, v8, v9
	ds_read2_b64 v[6:9], v91 offset0:160 offset1:162
	ds_read2_b64 v[156:159], v91 offset0:164 offset1:166
	v_add_u32_e32 v82, 0x1000, v129
	s_waitcnt lgkmcnt(1)
	v_mfma_f32_32x32x16_bf16 v[18:33], v[6:9], v[2:5], 0
	ds_read2_b64 v[6:9], v82 offset0:224 offset1:226
	v_cvt_pk_bf16_f32 v148, v148, v149
	v_cvt_pk_bf16_f32 v149, v150, v151
	v_cvt_pk_bf16_f32 v150, v152, v153
	v_cvt_pk_bf16_f32 v151, v154, v155
	ds_read2_b64 v[152:155], v82 offset0:228 offset1:230
	s_waitcnt lgkmcnt(0)
	v_mfma_f32_32x32x16_bf16 v[2:17], v[6:9], v[2:5], 0
	s_barrier
; DI f32x16 mfma(bf16x8 a, bf16x8 b, f32x16 c) { return __builtin_amdgcn_mfma_f32_32x32x16_bf16(a, b, c, 0, 0, 0); }
; DI void phase_mixb(const Prm& p, unsigned char* smem_raw, int S, int lgS, int& base) {
;     ...
;     for (int tt = 0; tt < 5; ++tt) {
; #pragma unroll
;       for (int e = 0; e < 4; ++e) {
;         const int c = lane + 64 * e, key = c >> 3, dch = c & 7;
;         int ik = i0 - 64 + 32 * tt + key;
;         ik = min(max(ik, 0), L - 1);
;         const u32x4 raw = *(const u32x4*)(p.bqkv + (size_t)(tokbase + (ik << lgd)) * 1152 + 768 + hc + dch * 8);
; #pragma unroll
;         for (int jj = 0; jj < 4; ++jj) {
;           vt[(dch * 8 + 2 * jj) * 40 + key] = (u16)(raw[jj] & 0xffffu);
;           vt[(dch * 8 + 2 * jj + 1) * 40 + key] = (u16)(raw[jj] >> 16);
;         }
;       }
;       __syncthreads();
; #pragma unroll
;       for (int u = 0; u < 2; ++u) {
;         u32x4 pk;
; #pragma unroll
;         for (int jj = 0; jj < 4; ++jj) pk[jj] = pack2(sc[tt][8 * u + 2 * jj], sc[tt][8 * u + 2 * jj + 1]);
;         const bf16x8 pf = __builtin_bit_cast(bf16x8, pk);
; #pragma unroll
;         for (int dt = 0; dt < 2; ++dt) {
;           const u16* vp = vt + (dt * 32 + lr) * 40 + 16 * u + 4 * lh;
;           u32x4 vv;
;           const u32x2 lo = *(const u32x2*)vp, hi = *(const u32x2*)(vp + 8);
;           vv[0] = lo[0]; vv[1] = lo[1]; vv[2] = hi[0]; vv[3] = hi[1];
;           oacc[dt] = mfma(__builtin_bit_cast(bf16x8, vv), pf, oacc[dt]);
;         }
;       }
;       __syncthreads();
	v_cvt_pk_bf16_f32 v74, v74, v75
	v_cvt_pk_bf16_f32 v75, v76, v77
	v_cvt_pk_bf16_f32 v76, v78, v80
	v_cvt_pk_bf16_f32 v77, v81, v85
	v_cvt_pk_bf16_f32 v59, v59, v60
	v_mfma_f32_32x32x16_bf16 v[18:33], v[156:159], v[148:151], v[18:33]
	v_cvt_pk_bf16_f32 v60, v61, v63
	v_cvt_pk_bf16_f32 v61, v64, v68
	v_cvt_pk_bf16_f32 v58, v57, v58
	v_cvt_pk_bf16_f32 v51, v51, v52
	v_cvt_pk_bf16_f32 v52, v53, v54
	v_cvt_pk_bf16_f32 v53, v55, v56
	v_cvt_pk_bf16_f32 v50, v49, v50
	v_mfma_f32_32x32x16_bf16 v[2:17], v[152:155], v[148:151], v[2:17]
	s_waitcnt vmcnt(15)
	ds_write_b16 v109, v176 offset:3328
	ds_write_b16_d16_hi v109, v176 offset:3408
	ds_write_b16 v109, v177 offset:3488
	ds_write_b16_d16_hi v109, v177 offset:3568
	ds_write_b16 v109, v178 offset:3648
	ds_write_b16_d16_hi v109, v178 offset:3728
	ds_write_b16 v109, v179 offset:3808
	ds_write_b16_d16_hi v109, v179 offset:3888
	s_waitcnt vmcnt(14)
	ds_write_b16 v109, v180 offset:3344
	ds_write_b16_d16_hi v109, v180 offset:3424
	ds_write_b16 v109, v181 offset:3504
	ds_write_b16_d16_hi v109, v181 offset:3584
	ds_write_b16 v109, v182 offset:3664
	ds_write_b16_d16_hi v109, v182 offset:3744
	ds_write_b16 v109, v183 offset:3824
	ds_write_b16_d16_hi v109, v183 offset:3904
	s_waitcnt vmcnt(13)
	ds_write_b16 v109, v184 offset:3360
	ds_write_b16_d16_hi v109, v184 offset:3440
	ds_write_b16 v109, v185 offset:3520
	ds_write_b16_d16_hi v109, v185 offset:3600
	ds_write_b16 v109, v186 offset:3680
	ds_write_b16_d16_hi v109, v186 offset:3760
	ds_write_b16 v109, v187 offset:3840
	ds_write_b16_d16_hi v109, v187 offset:3920
	s_waitcnt vmcnt(12)
	ds_write_b16 v109, v188 offset:3376
	ds_write_b16_d16_hi v109, v188 offset:3456
	ds_write_b16 v109, v189 offset:3536
	ds_write_b16_d16_hi v109, v189 offset:3616
	ds_write_b16 v109, v190 offset:3696
	ds_write_b16_d16_hi v109, v190 offset:3776
	ds_write_b16 v109, v191 offset:3856
	ds_write_b16_d16_hi v109, v191 offset:3936
	s_waitcnt lgkmcnt(0)
	s_barrier
	v_cvt_pk_bf16_f32 v150, v144, v145
	v_cvt_pk_bf16_f32 v151, v146, v147
	ds_read2_b64 v[144:147], v91 offset0:160 offset1:162
	ds_read2_b64 v[152:155], v91 offset0:164 offset1:166
	v_cvt_pk_bf16_f32 v148, v137, v140
	v_cvt_pk_bf16_f32 v149, v141, v143
	s_waitcnt lgkmcnt(1)
	s_nop 0
	v_mfma_f32_32x32x16_bf16 v[18:33], v[144:147], v[148:151], v[18:33]
	ds_read2_b64 v[144:147], v82 offset0:224 offset1:226
	ds_bpermute_b32 v40, v106, v39
	v_cvt_pk_bf16_f32 v43, v43, v44
	v_cvt_pk_bf16_f32 v44, v45, v46
	v_cvt_pk_bf16_f32 v45, v47, v48
	v_cvt_pk_bf16_f32 v42, v41, v42
	s_waitcnt lgkmcnt(1)
	v_mfma_f32_32x32x16_bf16 v[2:17], v[144:147], v[148:151], v[2:17]
	v_cvt_pk_bf16_f32 v145, v134, v135
	v_cvt_pk_bf16_f32 v146, v136, v138
	ds_read2_b64 v[134:137], v82 offset0:228 offset1:230
	v_cvt_pk_bf16_f32 v144, v92, v93
	v_cvt_pk_bf16_f32 v147, v139, v142
	s_waitcnt lgkmcnt(0)
	s_nop 0
	v_mfma_f32_32x32x16_bf16 v[2:17], v[134:137], v[144:147], v[2:17]
	s_barrier
	s_waitcnt vmcnt(11)
	ds_write_b16 v109, v192 offset:3328
	ds_write_b16_d16_hi v109, v192 offset:3408
	ds_write_b16 v109, v193 offset:3488
	ds_write_b16_d16_hi v109, v193 offset:3568
	ds_write_b16 v109, v194 offset:3648
	ds_write_b16_d16_hi v109, v194 offset:3728
	ds_write_b16 v109, v195 offset:3808
	ds_write_b16_d16_hi v109, v195 offset:3888
	s_waitcnt vmcnt(10)
	ds_write_b16 v109, v196 offset:3344
	ds_write_b16_d16_hi v109, v196 offset:3424
	ds_write_b16 v109, v197 offset:3504
	ds_write_b16_d16_hi v109, v197 offset:3584
	ds_write_b16 v109, v198 offset:3664
	ds_write_b16_d16_hi v109, v198 offset:3744
	ds_write_b16 v109, v199 offset:3824
	ds_write_b16_d16_hi v109, v199 offset:3904
	s_waitcnt vmcnt(9)
	ds_write_b16 v109, v200 offset:3360
	ds_write_b16_d16_hi v109, v200 offset:3440
	ds_write_b16 v109, v201 offset:3520
	ds_write_b16_d16_hi v109, v201 offset:3600
	ds_write_b16 v109, v202 offset:3680
	ds_write_b16_d16_hi v109, v202 offset:3760
	ds_write_b16 v109, v203 offset:3840
	ds_write_b16_d16_hi v109, v203 offset:3920
	v_mfma_f32_32x32x16_bf16 v[18:33], v[152:155], v[144:147], v[18:33]
	s_waitcnt vmcnt(8)
	ds_write_b16 v109, v204 offset:3376
	ds_write_b16_d16_hi v109, v204 offset:3456
	ds_write_b16 v109, v205 offset:3536
	ds_write_b16_d16_hi v109, v205 offset:3616
	ds_write_b16 v109, v206 offset:3696
	ds_write_b16_d16_hi v109, v206 offset:3776
	ds_write_b16 v109, v207 offset:3856
	ds_write_b16_d16_hi v109, v207 offset:3936
	s_waitcnt lgkmcnt(0)
	s_barrier
	v_cvt_pk_bf16_f32 v135, v84, v86
	v_cvt_pk_bf16_f32 v136, v87, v88
	v_cvt_pk_bf16_f32 v137, v89, v90
	ds_read2_b64 v[86:89], v91 offset0:160 offset1:162
	ds_read2_b64 v[138:141], v91 offset0:164 offset1:166
	v_cvt_pk_bf16_f32 v134, v79, v83
	ds_read2_b64 v[78:81], v82 offset0:228 offset1:230
	s_waitcnt lgkmcnt(2)
	v_mfma_f32_32x32x16_bf16 v[18:33], v[86:89], v[134:137], v[18:33]
	ds_read2_b64 v[86:89], v82 offset0:224 offset1:226
	s_waitcnt lgkmcnt(0)
	s_barrier
; DI f32x16 mfma(bf16x8 a, bf16x8 b, f32x16 c) { return __builtin_amdgcn_mfma_f32_32x32x16_bf16(a, b, c, 0, 0, 0); }
; DI void phase_mixb(const Prm& p, unsigned char* smem_raw, int S, int lgS, int& base) {
;     ...
;     for (int tt = 0; tt < 5; ++tt) {
; #pragma unroll
;       for (int e = 0; e < 4; ++e) {
;         const int c = lane + 64 * e, key = c >> 3, dch = c & 7;
;         int ik = i0 - 64 + 32 * tt + key;
;         ik = min(max(ik, 0), L - 1);
;         const u32x4 raw = *(const u32x4*)(p.bqkv + (size_t)(tokbase + (ik << lgd)) * 1152 + 768 + hc + dch * 8);
; #pragma unroll
;         for (int jj = 0; jj < 4; ++jj) {
;           vt[(dch * 8 + 2 * jj) * 40 + key] = (u16)(raw[jj] & 0xffffu);
;           vt[(dch * 8 + 2 * jj + 1) * 40 + key] = (u16)(raw[jj] >> 16);
;         }
;       }
;       __syncthreads();
; #pragma unroll
;       for (int u = 0; u < 2; ++u) {
;         u32x4 pk;
; #pragma unroll
;         for (int jj = 0; jj < 4; ++jj) pk[jj] = pack2(sc[tt][8 * u + 2 * jj], sc[tt][8 * u + 2 * jj + 1]);
;         const bf16x8 pf = __builtin_bit_cast(bf16x8, pk);
; #pragma unroll
;         for (int dt = 0; dt < 2; ++dt) {
;           const u16* vp = vt + (dt * 32 + lr) * 40 + 16 * u + 4 * lh;
;           u32x4 vv;
;           const u32x2 lo = *(const u32x2*)vp, hi = *(const u32x2*)(vp + 8);
;           vv[0] = lo[0]; vv[1] = lo[1]; vv[2] = hi[0]; vv[3] = hi[1];
;           oacc[dt] = mfma(__builtin_bit_cast(bf16x8, vv), pf, oacc[dt]);
;         }
;       }
;       __syncthreads();
;     }
;     const float inv = 1.f / sum;
; #pragma unroll
;     for (int dt = 0; dt < 2; ++dt)
; #pragma unroll
;       for (int q = 0; q < 4; ++q) {
;         float4 o;
;         o.x = oacc[dt][4 * q] * inv; o.y = oacc[dt][4 * q + 1] * inv; o.z = oacc[dt][4 * q + 2] * inv; o.w = oacc[dt][4 * q + 3] * inv;
;         *(float4*)(p.og + (size_t)qtok * 384 + hc + dt * 32 + 8 * q + 4 * lh) = o;
;       }
;     if (lh == 0) p.lse[(size_t)qtok * 6 + hd] = (mx + __log2f(sum)) * LN2;
	v_readlane_b32 s37, v253, 25
	v_mfma_f32_32x32x16_bf16 v[2:17], v[86:89], v[134:137], v[2:17]
	v_readlane_b32 s40, v253, 28
	v_readlane_b32 s41, v253, 29
	v_readlane_b32 s42, v253, 30
	v_readlane_b32 s43, v253, 31
	v_readlane_b32 s44, v253, 32
	v_readlane_b32 s45, v253, 33
	v_readlane_b32 s46, v253, 34
	v_mfma_f32_32x32x16_bf16 v[18:33], v[138:141], v[74:77], v[18:33]
	v_readlane_b32 s47, v253, 35
	v_readlane_b32 s48, v253, 36
	v_readlane_b32 s49, v253, 37
	v_readlane_b32 s50, v253, 38
	v_readlane_b32 s51, v253, 39
	v_mfma_f32_32x32x16_bf16 v[2:17], v[78:81], v[74:77], v[2:17]
	s_waitcnt vmcnt(7)
	ds_write_b16 v109, v208 offset:3328
	ds_write_b16_d16_hi v109, v208 offset:3408
	ds_write_b16 v109, v209 offset:3488
	ds_write_b16_d16_hi v109, v209 offset:3568
	ds_write_b16 v109, v210 offset:3648
	ds_write_b16_d16_hi v109, v210 offset:3728
	ds_write_b16 v109, v211 offset:3808
	ds_write_b16_d16_hi v109, v211 offset:3888
	s_waitcnt vmcnt(6)
	ds_write_b16 v109, v212 offset:3344
	ds_write_b16_d16_hi v109, v212 offset:3424
	ds_write_b16 v109, v213 offset:3504
	ds_write_b16_d16_hi v109, v213 offset:3584
	ds_write_b16 v109, v214 offset:3664
	ds_write_b16_d16_hi v109, v214 offset:3744
	ds_write_b16 v109, v215 offset:3824
	ds_write_b16_d16_hi v109, v215 offset:3904
	s_waitcnt vmcnt(5)
	ds_write_b16 v109, v216 offset:3360
	ds_write_b16_d16_hi v109, v216 offset:3440
	ds_write_b16 v109, v217 offset:3520
	ds_write_b16_d16_hi v109, v217 offset:3600
	ds_write_b16 v109, v218 offset:3680
	ds_write_b16_d16_hi v109, v218 offset:3760
	ds_write_b16 v109, v219 offset:3840
	ds_write_b16_d16_hi v109, v219 offset:3920
	s_waitcnt vmcnt(4)
	ds_write_b16 v109, v220 offset:3376
	ds_write_b16_d16_hi v109, v220 offset:3456
	ds_write_b16 v109, v221 offset:3536
	ds_write_b16_d16_hi v109, v221 offset:3616
	ds_write_b16 v109, v222 offset:3696
	ds_write_b16_d16_hi v109, v222 offset:3776
	ds_write_b16 v109, v223 offset:3856
	ds_write_b16_d16_hi v109, v223 offset:3936
	s_waitcnt lgkmcnt(0)
	s_barrier
	v_cvt_pk_bf16_f32 v76, v70, v71
	v_cvt_pk_bf16_f32 v77, v72, v73
	ds_read2_b64 v[70:73], v91 offset0:160 offset1:162
	ds_read2_b64 v[78:81], v91 offset0:164 offset1:166
	v_cvt_pk_bf16_f32 v74, v62, v65
	v_cvt_pk_bf16_f32 v75, v67, v69
	ds_read2_b64 v[62:65], v82 offset0:228 offset1:230
	s_waitcnt lgkmcnt(2)
	v_mfma_f32_32x32x16_bf16 v[18:33], v[70:73], v[74:77], v[18:33]
	ds_read2_b64 v[70:73], v82 offset0:224 offset1:226
	s_waitcnt lgkmcnt(0)
	s_barrier
	v_mfma_f32_32x32x16_bf16 v[2:17], v[70:73], v[74:77], v[2:17]
	v_mfma_f32_32x32x16_bf16 v[18:33], v[78:81], v[58:61], v[18:33]
	v_mfma_f32_32x32x16_bf16 v[2:17], v[62:65], v[58:61], v[2:17]
	s_waitcnt vmcnt(3)
	ds_write_b16 v109, v226 offset:3328
	ds_write_b16_d16_hi v109, v226 offset:3408
	ds_write_b16 v109, v227 offset:3488
	ds_write_b16_d16_hi v109, v227 offset:3568
	ds_write_b16 v109, v228 offset:3648
	ds_write_b16_d16_hi v109, v228 offset:3728
	ds_write_b16 v109, v229 offset:3808
	ds_write_b16_d16_hi v109, v229 offset:3888
	s_waitcnt vmcnt(2)
	ds_write_b16 v109, v234 offset:3344
	ds_write_b16_d16_hi v109, v234 offset:3424
	ds_write_b16 v109, v235 offset:3504
	ds_write_b16_d16_hi v109, v235 offset:3584
	ds_write_b16 v109, v236 offset:3664
	ds_write_b16_d16_hi v109, v236 offset:3744
	ds_write_b16 v109, v237 offset:3824
	ds_write_b16_d16_hi v109, v237 offset:3904
	s_waitcnt vmcnt(1)
	ds_write_b16 v109, v244 offset:3360
	ds_write_b16_d16_hi v109, v244 offset:3440
	ds_write_b16 v109, v245 offset:3520
	ds_write_b16_d16_hi v109, v245 offset:3600
	ds_write_b16 v109, v246 offset:3680
	ds_write_b16_d16_hi v109, v246 offset:3760
	ds_write_b16 v109, v247 offset:3840
	ds_write_b16_d16_hi v109, v247 offset:3920
	s_waitcnt vmcnt(0)
	ds_write_b16 v109, v248 offset:3376
	ds_write_b16_d16_hi v109, v248 offset:3456
	ds_write_b16 v109, v249 offset:3536
	ds_write_b16_d16_hi v109, v249 offset:3616
	ds_write_b16 v109, v250 offset:3696
	ds_write_b16_d16_hi v109, v250 offset:3776
	ds_write_b16 v109, v251 offset:3856
	ds_write_b16_d16_hi v109, v251 offset:3936
	s_waitcnt lgkmcnt(0)
	s_barrier
	ds_read2_b64 v[54:57], v91 offset0:160 offset1:162
	ds_read2_b64 v[58:61], v91 offset0:164 offset1:166
	s_waitcnt lgkmcnt(1)
	v_mfma_f32_32x32x16_bf16 v[18:33], v[54:57], v[50:53], v[18:33]
	ds_read2_b64 v[54:57], v82 offset0:224 offset1:226
	ds_read2_b64 v[46:49], v82 offset0:228 offset1:230
	v_add_f32_e32 v34, v39, v40
	v_div_scale_f32 v35, s[2:3], v34, v34, 1.0
	v_rcp_f32_e32 v37, v35
	s_waitcnt lgkmcnt(0)
	v_mfma_f32_32x32x16_bf16 v[2:17], v[54:57], v[50:53], v[2:17]
	v_fma_f32 v38, -v35, v37, 1.0
	v_fmac_f32_e32 v37, v38, v37
	v_div_scale_f32 v38, vcc, 1.0, v34, 1.0
	v_mul_f32_e32 v39, v38, v37
	v_fma_f32 v40, -v35, v39, v38
	v_fmac_f32_e32 v39, v40, v37
	v_mfma_f32_32x32x16_bf16 v[18:33], v[58:61], v[42:45], v[18:33]
	v_fma_f32 v35, -v35, v39, v38
	v_mov_b64_e32 v[40:41], s[24:25]
	v_div_fmas_f32 v35, v35, v37, v39
	v_mad_i64_i32 v[40:41], s[2:3], v130, s83, v[40:41]
	v_div_fixup_f32 v38, v35, v34, 1.0
	v_lshl_add_u64 v[40:41], v[100:101], 2, v[40:41]
	v_mfma_f32_32x32x16_bf16 v[2:17], v[46:49], v[42:45], v[2:17]
	v_lshlrev_b32_e32 v42, 2, v94
	v_mov_b32_e32 v43, v1
	v_lshl_add_u64 v[40:41], v[40:41], 0, v[42:43]
	s_nop 1
	v_mul_f32_e64 v18, v38, v18
	v_mul_f32_e64 v19, v38, v19
	v_pk_mul_f32 v[20:21], v[38:39], v[20:21] op_sel_hi:[0,1]
	s_barrier
	s_nop 2
	v_pk_mul_f32 v[2:3], v[38:39], v[2:3] op_sel_hi:[0,1]
	v_pk_mul_f32 v[4:5], v[38:39], v[4:5] op_sel_hi:[0,1]
	global_store_dwordx4 v[40:41], v[18:21], off
	global_store_dwordx4 v[40:41], v[2:5], off offset:128
	s_nop 0
	v_pk_mul_f32 v[18:19], v[38:39], v[22:23] op_sel_hi:[0,1]
	v_pk_mul_f32 v[20:21], v[38:39], v[24:25] op_sel_hi:[0,1]
	v_pk_mul_f32 v[2:3], v[38:39], v[6:7] op_sel_hi:[0,1]
	v_pk_mul_f32 v[4:5], v[38:39], v[8:9] op_sel_hi:[0,1]
	global_store_dwordx4 v[40:41], v[18:21], off offset:32
	global_store_dwordx4 v[40:41], v[2:5], off offset:160
	s_nop 0
	v_pk_mul_f32 v[18:19], v[38:39], v[26:27] op_sel_hi:[0,1]
	v_pk_mul_f32 v[20:21], v[38:39], v[28:29] op_sel_hi:[0,1]
	v_pk_mul_f32 v[2:3], v[38:39], v[10:11] op_sel_hi:[0,1]
	v_pk_mul_f32 v[4:5], v[38:39], v[12:13] op_sel_hi:[0,1]
	global_store_dwordx4 v[40:41], v[18:21], off offset:64
	global_store_dwordx4 v[40:41], v[2:5], off offset:192
	s_nop 0
	v_pk_mul_f32 v[18:19], v[38:39], v[30:31] op_sel_hi:[0,1]
	v_pk_mul_f32 v[20:21], v[38:39], v[32:33] op_sel_hi:[0,1]
	v_pk_mul_f32 v[2:3], v[38:39], v[14:15] op_sel_hi:[0,1]
	v_pk_mul_f32 v[4:5], v[38:39], v[16:17] op_sel_hi:[0,1]
	global_store_dwordx4 v[40:41], v[18:21], off offset:96
	global_store_dwordx4 v[40:41], v[2:5], off offset:224
	s_and_saveexec_b64 s[2:3], s[0:1]
	s_cbranch_execz .LBB0_1836
	v_log_f32_e32 v4, v34
	v_ashrrev_i32_e32 v99, 31, v98
	v_mad_i64_i32 v[2:3], s[4:5], v130, 24, s[26:27]
	v_add_f32_e32 v4, v36, v4
	v_mul_f32_e32 v4, 0x3f317218, v4
	v_lshl_add_u64 v[2:3], v[98:99], 2, v[2:3]
	global_store_dword v[2:3], v4, off
	s_branch .LBB0_1836
